# adds: attention row-sum adds moved into the PV phase gaps (same summation order), GEMM code kept at its original 64-byte alignment
# speedup vs baseline: 1.0045x; 1.0045x over previous
.LBB0_90:
	v_add_f32_e32 v227, v227, v246
	s_lshl_b32 s21, s28, 1
	v_add_u32_e32 v213, s21, v225
	ds_read_b64_tr_b16 v[208:209], v213 offset:24576
	ds_read_b64_tr_b16 v[210:211], v213 offset:25088
	s_waitcnt lgkmcnt(9)
	v_mfma_f32_32x32x16_bf16 v[128:143], v[204:207], v[172:175], v[64:79]
	v_cvt_pk_bf16_f32 v164, v96, v97
	v_cvt_pk_bf16_f32 v165, v98, v99
	ds_read_b64_tr_b16 v[204:205], v213 offset:28672
	ds_read_b64_tr_b16 v[206:207], v213 offset:29184
	s_waitcnt lgkmcnt(10)
	v_mfma_f32_32x32x16_bf16 v[128:143], v[196:199], v[168:171], v[128:143]
	v_cvt_pk_bf16_f32 v166, v100, v101
	v_cvt_pk_bf16_f32 v167, v102, v103
	ds_read_b64_tr_b16 v[96:97], v213 offset:25600
	ds_read_b64_tr_b16 v[98:99], v213 offset:26112
	s_waitcnt lgkmcnt(11)
	v_mfma_f32_32x32x16_bf16 v[128:143], v[188:191], v[160:163], v[128:143]
	v_cvt_pk_bf16_f32 v156, v104, v105
	v_cvt_pk_bf16_f32 v157, v106, v107
	ds_read_b64_tr_b16 v[100:101], v213 offset:29696
	ds_read_b64_tr_b16 v[102:103], v213 offset:30208
	s_waitcnt lgkmcnt(12)
	v_mfma_f32_32x32x16_bf16 v[128:143], v[180:183], v[152:155], v[128:143]
	v_cvt_pk_bf16_f32 v158, v108, v109
	v_cvt_pk_bf16_f32 v159, v110, v111
	ds_read_b64_tr_b16 v[104:105], v213 offset:26624
	ds_read_b64_tr_b16 v[106:107], v213 offset:27136
	s_waitcnt lgkmcnt(13)
	v_mfma_f32_32x32x16_bf16 v[112:127], v[200:203], v[172:175], v[64:79]
	v_cvt_pk_bf16_f32 v148, v80, v81
	v_cvt_pk_bf16_f32 v149, v82, v83
	ds_read_b64_tr_b16 v[108:109], v213 offset:30720
	ds_read_b64_tr_b16 v[110:111], v213 offset:31232
	s_waitcnt lgkmcnt(14)
	v_mfma_f32_32x32x16_bf16 v[112:127], v[192:195], v[168:171], v[112:127]
	v_cvt_pk_bf16_f32 v150, v84, v85
	v_cvt_pk_bf16_f32 v151, v86, v87
	ds_read_b64_tr_b16 v[84:85], v213 offset:27648
	ds_read_b64_tr_b16 v[86:87], v213 offset:28160
	s_waitcnt lgkmcnt(14)
	v_mfma_f32_32x32x16_bf16 v[112:127], v[184:187], v[160:163], v[112:127]
	v_cvt_pk_bf16_f32 v144, v88, v89
	v_cvt_pk_bf16_f32 v145, v90, v91
	ds_read_b64_tr_b16 v[88:89], v213 offset:31744
	ds_read_b64_tr_b16 v[90:91], v213 offset:32256
	v_mfma_f32_32x32x16_bf16 v[112:127], v[176:179], v[152:155], v[112:127]
	v_cvt_pk_bf16_f32 v146, v92, v93
	v_cvt_pk_bf16_f32 v147, v94, v95
	v_lshl_add_u64 v[218:219], v[230:231], 0, s[36:37]
	v_lshl_add_u64 v[80:81], v[218:219], 0, s[92:93]
	s_add_i32 s21, s27, s18
	v_lshl_add_u64 v[216:217], v[214:215], 0, s[36:37]
	s_mov_b32 s24, m0
	s_mov_b32 m0, s21
	s_nop 0
	global_load_lds_dwordx4 v[80:81], off
	s_mov_b32 m0, s24
	v_lshl_add_u64 v[80:81], v[216:217], 0, s[0:1]
	s_lshl_b32 s21, s25, 1
	s_add_i32 s21, s21, s19
	s_mov_b32 s24, m0
	s_mov_b32 m0, s21
	s_nop 0
	global_load_lds_dwordx4 v[80:81], off
	s_mov_b32 m0, s24
	v_lshl_add_u64 v[80:81], v[216:217], 0, s[68:69]
	s_addk_i32 s21, 0x2000
	s_mov_b32 s24, m0
	s_mov_b32 m0, s21
	s_nop 0
	global_load_lds_dwordx4 v[80:81], off
	s_mov_b32 m0, s24
	v_max_f32_e32 v80, v129, v129
	v_max_f32_e32 v81, v128, v128
	v_max_f32_e32 v80, v81, v80
	v_max3_f32 v81, v130, v131, v113
	v_max3_f32 v80, v80, v112, v114
	v_max3_f32 v80, v80, v115, v132
	v_max3_f32 v81, v81, v134, v135
	v_max3_f32 v80, v80, v133, v116
	v_max3_f32 v81, v81, v118, v119
	v_max3_f32 v80, v80, v117, v136
	v_max3_f32 v81, v81, v138, v139
	v_max3_f32 v80, v80, v137, v120
	v_max3_f32 v81, v81, v122, v123
	v_max3_f32 v80, v80, v121, v140
	v_max3_f32 v81, v81, v142, v143
	v_max3_f32 v80, v80, v141, v124
	v_max3_f32 v81, v81, v126, v127
	v_max3_f32 v80, v80, v125, v81
	v_mov_b32_e32 v81, v80
	s_nop 1
	v_permlane32_swap_b32_e32 v80, v81
	v_max_f32_e32 v81, v81, v81
	v_max_f32_e32 v80, v80, v80
	v_max_f32_e32 v80, v80, v81
	v_cmp_lt_f32_e32 vcc, s74, v80
	s_cmp_lg_u64 vcc, 0
	s_cselect_b64 s[38:39], -1, 0
	s_cbranch_vccnz .LBB0_98

.LBB0_93:
	v_add_f32_e32 v227, v227, v246
	s_add_i32 s21, s25, 0x2000
	s_cmpk_lg_i32 s25, 0x4000
	s_cselect_b32 s21, s21, 0
	s_lshl_b32 s24, s27, 1
	v_add_u32_e32 v228, s24, v225
	ds_read_b64_tr_b16 v[204:205], v228 offset:24576
	ds_read_b64_tr_b16 v[206:207], v228 offset:25088
	v_mfma_f32_32x32x16_bf16 v[96:111], v[80:83], v[172:175], v[64:79]
	v_cvt_pk_bf16_f32 v164, v128, v129
	v_cvt_pk_bf16_f32 v165, v130, v131
	ds_read_b64_tr_b16 v[208:209], v228 offset:28672
	ds_read_b64_tr_b16 v[210:211], v228 offset:29184
	v_mfma_f32_32x32x16_bf16 v[96:111], v[200:203], v[168:171], v[96:111]
	v_cvt_pk_bf16_f32 v166, v132, v133
	v_cvt_pk_bf16_f32 v167, v134, v135
	ds_read_b64_tr_b16 v[128:129], v228 offset:25600
	ds_read_b64_tr_b16 v[130:131], v228 offset:26112
	v_mfma_f32_32x32x16_bf16 v[96:111], v[188:191], v[160:163], v[96:111]
	v_cvt_pk_bf16_f32 v156, v136, v137
	v_cvt_pk_bf16_f32 v157, v138, v139
	ds_read_b64_tr_b16 v[132:133], v228 offset:29696
	ds_read_b64_tr_b16 v[134:135], v228 offset:30208
	v_mfma_f32_32x32x16_bf16 v[96:111], v[180:183], v[152:155], v[96:111]
	v_cvt_pk_bf16_f32 v158, v140, v141
	v_cvt_pk_bf16_f32 v159, v142, v143
	ds_read_b64_tr_b16 v[136:137], v228 offset:26624
	ds_read_b64_tr_b16 v[138:139], v228 offset:27136
	v_mfma_f32_32x32x16_bf16 v[80:95], v[196:199], v[172:175], v[64:79]
	v_cvt_pk_bf16_f32 v148, v112, v113
	v_cvt_pk_bf16_f32 v149, v114, v115
	ds_read_b64_tr_b16 v[112:113], v228 offset:30720
	ds_read_b64_tr_b16 v[114:115], v228 offset:31232
	v_mfma_f32_32x32x16_bf16 v[80:95], v[192:195], v[168:171], v[80:95]
	v_cvt_pk_bf16_f32 v150, v116, v117
	v_cvt_pk_bf16_f32 v151, v118, v119
	ds_read_b64_tr_b16 v[116:117], v228 offset:27648
	ds_read_b64_tr_b16 v[118:119], v228 offset:28160
	v_mfma_f32_32x32x16_bf16 v[80:95], v[184:187], v[160:163], v[80:95]
	v_cvt_pk_bf16_f32 v144, v120, v121
	v_cvt_pk_bf16_f32 v145, v122, v123
	ds_read_b64_tr_b16 v[120:121], v228 offset:31744
	ds_read_b64_tr_b16 v[122:123], v228 offset:32256
	v_mfma_f32_32x32x16_bf16 v[80:95], v[176:179], v[152:155], v[80:95]
	v_cvt_pk_bf16_f32 v146, v124, v125
	v_cvt_pk_bf16_f32 v147, v126, v127
	s_mov_b64 s[28:29], 0x460000
	v_lshl_add_u64 v[124:125], v[218:219], 0, s[28:29]
	s_add_i32 s24, s25, s18
	s_mov_b64 s[28:29], 0x12aa1000
	s_mov_b32 s27, m0
	s_mov_b32 m0, s24
	s_nop 0
	global_load_lds_dwordx4 v[124:125], off
	s_mov_b32 m0, s27
	v_lshl_add_u64 v[124:125], v[216:217], 0, s[28:29]
	s_lshl_b32 s24, s21, 1
	s_mov_b64 s[28:29], 0x12aa1080
	s_add_i32 s24, s24, s19
	s_mov_b32 s27, m0
	s_mov_b32 m0, s24
	s_nop 0
	global_load_lds_dwordx4 v[124:125], off
	s_mov_b32 m0, s27
	v_lshl_add_u64 v[124:125], v[216:217], 0, s[28:29]
	s_addk_i32 s24, 0x2000
	s_mov_b32 s27, m0
	s_mov_b32 m0, s24
	s_nop 0
	global_load_lds_dwordx4 v[124:125], off
	s_mov_b32 m0, s27
	v_max_f32_e32 v124, v97, v97
	v_max_f32_e32 v125, v96, v96
	v_max_f32_e32 v124, v125, v124
	v_max3_f32 v125, v98, v99, v81
	v_max3_f32 v124, v124, v80, v82
	v_max3_f32 v124, v124, v83, v100
	v_max3_f32 v125, v125, v102, v103
	v_max3_f32 v124, v124, v101, v84
	v_max3_f32 v125, v125, v86, v87
	v_max3_f32 v124, v124, v85, v104
	v_max3_f32 v125, v125, v106, v107
	v_max3_f32 v124, v124, v105, v88
	v_max3_f32 v125, v125, v90, v91
	v_max3_f32 v124, v124, v89, v108
	v_max3_f32 v125, v125, v110, v111
	v_max3_f32 v124, v124, v109, v92
	v_max3_f32 v125, v125, v94, v95
	v_max3_f32 v124, v124, v93, v125
	v_mov_b32_e32 v125, v124
	s_nop 1
	v_permlane32_swap_b32_e32 v124, v125
	v_max_f32_e32 v125, v125, v125
	v_max_f32_e32 v124, v124, v124
	v_max_f32_e32 v124, v124, v125
	v_cmp_lt_f32_e32 vcc, s74, v124
	s_cmp_lg_u64 vcc, 0
	s_cselect_b64 s[38:39], -1, 0
	s_cbranch_vccnz .LBB0_101

.LBB0_163:
	v_max_f32_e32 v96, v96, v96
	v_max_f32_e32 v113, 0, v96
	v_add_f32_e32 v96, v223, v113
	v_xor_b32_e32 v96, 0x80000000, v96
	v_mov_b32_e32 v97, v96
	v_mov_b32_e32 v98, v96
	v_mov_b32_e32 v99, v96
	v_mov_b32_e32 v100, v96
	v_mov_b32_e32 v101, v96
	v_mov_b32_e32 v102, v96
	v_mov_b32_e32 v103, v96
	v_mov_b32_e32 v104, v96
	v_mov_b32_e32 v105, v96
	v_mov_b32_e32 v106, v96
	v_mov_b32_e32 v107, v96
	v_mov_b32_e32 v108, v96
	v_mov_b32_e32 v109, v96
	v_mov_b32_e32 v110, v96
	v_mov_b32_e32 v111, v96
	v_cmp_gt_u32_e32 vcc, 32, v247
	v_exp_f32_e64 v96, -v113
	s_and_saveexec_b64 s[6:7], vcc
	ds_write_b32 v245, v96
	s_or_b64 exec, exec, s[6:7]
	v_sub_f32_e32 v95, v95, v113
	v_sub_f32_e32 v94, v94, v113
	v_sub_f32_e32 v93, v93, v113
	v_sub_f32_e32 v92, v92, v113
	v_sub_f32_e32 v91, v91, v113
	v_sub_f32_e32 v90, v90, v113
	v_sub_f32_e32 v89, v89, v113
	v_sub_f32_e32 v88, v88, v113
	v_sub_f32_e32 v87, v87, v113
	v_sub_f32_e32 v86, v86, v113
	v_sub_f32_e32 v85, v85, v113
	v_sub_f32_e32 v84, v84, v113
	v_sub_f32_e32 v83, v83, v113
	v_sub_f32_e32 v82, v82, v113
	v_sub_f32_e32 v81, v81, v113
	v_sub_f32_e32 v80, v80, v113
	v_sub_f32_e32 v79, v79, v113
	v_sub_f32_e32 v78, v78, v113
	v_sub_f32_e32 v77, v77, v113
	v_sub_f32_e32 v76, v76, v113
	v_sub_f32_e32 v75, v75, v113
	v_sub_f32_e32 v74, v74, v113
	v_sub_f32_e32 v73, v73, v113
	v_sub_f32_e32 v72, v72, v113
	v_sub_f32_e32 v71, v71, v113
	v_sub_f32_e32 v70, v70, v113
	v_sub_f32_e32 v69, v69, v113
	v_sub_f32_e32 v68, v68, v113
	v_sub_f32_e32 v67, v67, v113
	v_sub_f32_e32 v66, v66, v113
	v_sub_f32_e32 v65, v65, v113
	v_sub_f32_e32 v64, v64, v113
	v_mul_f32_e32 v112, v112, v96
	s_branch .LBB0_108
	s_nop 0
	s_nop 0
